# GEMM unit start: accumulators cleared with 64-bit moves (64 instead of 128 instructions per wave per unit)
# speedup vs baseline: 1.0049x; 1.0049x over previous
; template <class Epi, class Sched, bool ALIGN_EPI = false, bool SP2 = false>
; __device__ __forceinline__ void gemm_phase(PG8_LAS unsigned char* lds, const Gemm g, const Sched& S, const Epi& E, const int tid) {
;     ...
;         const bool has_next = S.next(ui + 1, nxt);
;         const char* nA = has_next ? (const char*)g.A + (size_t)nxt.pm * tstep : cA; const char* nB = has_next ? (const char*)g.Bt + (size_t)nxt.pn * tstep : cB;
;         for (int t = 0; t < nt; t += 2) {
;             const bool last = (t == nt - 2);
;             const char* a1 = cA + (size_t)(t + 1) * kstep;
;             const char* a2 = last ? nA : cA + (size_t)(t + 2) * kstep; const char* b2 = last ? nB : cB + (size_t)(t + 2) * kstep;
;     ...
; #pragma unroll
;         for (int a = 0; a < 2; ++a)
; #pragma unroll
;             for (int b = 0; b < 2; ++b)
; #pragma unroll
;                 for (int m = 0; m < 4; ++m)
; #pragma unroll
;                     for (int n = 0; n < 2; ++n) acc[a][b][m][n] = (f32x4){0.f, 0.f, 0.f, 0.f};
.LBB0_61:
	s_ashr_i32 s39, s38, 31
	s_lshl_b64 s[36:37], s[38:39], 19
	s_add_u32 s40, s94, s36
	s_addc_u32 s41, s95, s37
	s_and_b64 s[36:37], exec, s[2:3]
	s_cselect_b32 s39, s31, s41
	s_cselect_b32 s62, s30, s40
	s_ashr_i32 s11, s10, 31
	s_lshl_b64 s[36:37], s[10:11], 19
	s_add_u32 s52, s56, s36
	s_addc_u32 s53, s57, s37
	s_and_b64 s[36:37], exec, s[2:3]
	s_cselect_b32 s11, s5, s53
	s_cselect_b32 s63, s4, s52
	s_add_u32 vcc_lo, s30, 0x40080
	s_addc_u32 vcc_hi, s31, 0
	s_add_u32 s30, s4, 0x100
	v_mov_b32_e32 v2, 0
	s_addc_u32 s31, s5, 0
	s_mov_b32 s64, -2
	s_waitcnt lgkmcnt(0)
	v_mov_b32_e32 v3, v2
	v_mov_b64_e32 v[4:5], 0
	v_mov_b64_e32 v[6:7], 0
	v_mov_b64_e32 v[8:9], 0
	v_mov_b64_e32 v[10:11], 0
	v_mov_b64_e32 v[12:13], 0
	v_mov_b64_e32 v[14:15], 0
	v_mov_b64_e32 v[16:17], 0
	v_mov_b64_e32 v[18:19], 0
	v_mov_b64_e32 v[20:21], 0
	v_mov_b64_e32 v[22:23], 0
	v_mov_b64_e32 v[24:25], 0
	v_mov_b64_e32 v[26:27], 0
	v_mov_b64_e32 v[28:29], 0
	v_mov_b64_e32 v[30:31], 0
	v_mov_b64_e32 v[32:33], 0
	v_mov_b64_e32 v[34:35], 0
	v_mov_b64_e32 v[36:37], 0
	v_mov_b64_e32 v[38:39], 0
	v_mov_b64_e32 v[40:41], 0
	v_mov_b64_e32 v[42:43], 0
	v_mov_b64_e32 v[44:45], 0
	v_mov_b64_e32 v[46:47], 0
	v_mov_b64_e32 v[48:49], 0
	v_mov_b64_e32 v[50:51], 0
	v_mov_b64_e32 v[52:53], 0
	v_mov_b64_e32 v[54:55], 0
	v_mov_b64_e32 v[56:57], 0
	v_mov_b64_e32 v[58:59], 0
	v_mov_b64_e32 v[60:61], 0
	v_mov_b64_e32 v[74:75], 0
	v_mov_b64_e32 v[76:77], 0
	v_mov_b64_e32 v[82:83], 0
	v_mov_b64_e32 v[84:85], 0
	v_mov_b64_e32 v[86:87], 0
	v_mov_b64_e32 v[88:89], 0
	v_mov_b64_e32 v[90:91], 0
	v_mov_b64_e32 v[92:93], 0
	v_mov_b64_e32 v[94:95], 0
	v_mov_b64_e32 v[96:97], 0
	v_mov_b64_e32 v[98:99], 0
	v_mov_b64_e32 v[100:101], 0
	v_mov_b64_e32 v[102:103], 0
	v_mov_b64_e32 v[104:105], 0
	v_mov_b64_e32 v[106:107], 0
	v_mov_b64_e32 v[108:109], 0
	v_mov_b64_e32 v[110:111], 0
	v_mov_b64_e32 v[112:113], 0
	v_mov_b64_e32 v[114:115], 0
	v_mov_b64_e32 v[116:117], 0
	v_mov_b64_e32 v[118:119], 0
	v_mov_b64_e32 v[120:121], 0
	v_mov_b64_e32 v[122:123], 0
	v_mov_b64_e32 v[124:125], 0
	v_mov_b64_e32 v[126:127], 0
	v_mov_b64_e32 v[128:129], 0
	v_mov_b64_e32 v[130:131], 0
	v_mov_b64_e32 v[132:133], 0
	v_mov_b64_e32 v[134:135], 0
	v_mov_b64_e32 v[136:137], 0
	v_mov_b64_e32 v[138:139], 0
	v_mov_b64_e32 v[140:141], 0
	v_mov_b64_e32 v[142:143], 0
	v_mov_b64_e32 v[144:145], 0

; template <class Epi, class Sched, bool ALIGN_EPI = false, bool SP2 = false>
; __device__ __forceinline__ void gemm_phase(PG8_LAS unsigned char* lds, const Gemm g, const Sched& S, const Epi& E, const int tid) {
;     ...
;         const bool has_next = S.next(ui + 1, nxt);
;         const char* nA = has_next ? (const char*)g.A + (size_t)nxt.pm * tstep : cA; const char* nB = has_next ? (const char*)g.Bt + (size_t)nxt.pn * tstep : cB;
;         for (int t = 0; t < nt; t += 2) {
;             const bool last = (t == nt - 2);
;             const char* a1 = cA + (size_t)(t + 1) * kstep;
;             const char* a2 = last ? nA : cA + (size_t)(t + 2) * kstep; const char* b2 = last ? nB : cB + (size_t)(t + 2) * kstep;
;     ...
; #pragma unroll
;         for (int a = 0; a < 2; ++a)
; #pragma unroll
;             for (int b = 0; b < 2; ++b)
; #pragma unroll
;                 for (int m = 0; m < 4; ++m)
; #pragma unroll
;                     for (int n = 0; n < 2; ++n) acc[a][b][m][n] = (f32x4){0.f, 0.f, 0.f, 0.f};
.LBB0_125:
	s_ashr_i32 s11, s10, 31
	s_lshl_b64 s[0:1], s[10:11], 19
	v_readlane_b32 s44, v250, 34
	v_readlane_b32 s45, v250, 35
	s_add_u32 s0, s44, s0
	s_addc_u32 s1, s45, s1
	s_and_b64 s[52:53], s[8:9], exec
	s_cselect_b32 s11, s1, s37
	s_cselect_b32 s39, s0, s36
	s_ashr_i32 s41, s40, 31
	s_lshl_b64 s[52:53], s[40:41], 19
	v_readlane_b32 s41, v252, 47
	s_add_u32 s52, s41, s52
	v_readlane_b32 s41, v252, 48
	s_addc_u32 s53, s41, s53
	s_and_b64 s[60:61], s[8:9], exec
	s_cselect_b32 s41, s53, s31
	s_cselect_b32 s60, s52, s30
	s_add_u32 s88, s36, 0x40080
	s_addc_u32 s89, s37, 0
	s_add_u32 s30, s30, 0x100
	v_mov_b32_e32 v2, 0
	s_addc_u32 s31, s31, 0
	s_mov_b32 s61, -2
	s_waitcnt lgkmcnt(0)
	v_mov_b32_e32 v3, v2
	v_mov_b64_e32 v[4:5], 0
	v_mov_b64_e32 v[6:7], 0
	v_mov_b64_e32 v[8:9], 0
	v_mov_b64_e32 v[10:11], 0
	v_mov_b64_e32 v[12:13], 0
	v_mov_b64_e32 v[14:15], 0
	v_mov_b64_e32 v[16:17], 0
	v_mov_b64_e32 v[18:19], 0
	v_mov_b64_e32 v[20:21], 0
	v_mov_b64_e32 v[22:23], 0
	v_mov_b64_e32 v[24:25], 0
	v_mov_b64_e32 v[42:43], 0
	v_mov_b64_e32 v[44:45], 0
	v_mov_b64_e32 v[46:47], 0
	v_mov_b64_e32 v[48:49], 0
	v_mov_b64_e32 v[50:51], 0
	v_mov_b64_e32 v[52:53], 0
	v_mov_b64_e32 v[54:55], 0
	v_mov_b64_e32 v[56:57], 0
	v_mov_b64_e32 v[74:75], 0
	v_mov_b64_e32 v[76:77], 0
	v_mov_b64_e32 v[78:79], 0
	v_mov_b64_e32 v[80:81], 0
	v_mov_b64_e32 v[82:83], 0
	v_mov_b64_e32 v[84:85], 0
	v_mov_b64_e32 v[86:87], 0
	v_mov_b64_e32 v[88:89], 0
	v_mov_b64_e32 v[90:91], 0
	v_mov_b64_e32 v[92:93], 0
	v_mov_b64_e32 v[94:95], 0
	v_mov_b64_e32 v[96:97], 0
	v_mov_b64_e32 v[98:99], 0
	v_mov_b64_e32 v[100:101], 0
	v_mov_b64_e32 v[102:103], 0
	v_mov_b64_e32 v[104:105], 0
	v_mov_b64_e32 v[106:107], 0
	v_mov_b64_e32 v[108:109], 0
	v_mov_b64_e32 v[110:111], 0
	v_mov_b64_e32 v[112:113], 0
	v_mov_b64_e32 v[114:115], 0
	v_mov_b64_e32 v[116:117], 0
	v_mov_b64_e32 v[118:119], 0
	v_mov_b64_e32 v[120:121], 0
	v_mov_b64_e32 v[122:123], 0
	v_mov_b64_e32 v[124:125], 0
	v_mov_b64_e32 v[126:127], 0
	v_mov_b64_e32 v[128:129], 0
	v_mov_b64_e32 v[130:131], 0
	v_mov_b64_e32 v[132:133], 0
	v_mov_b64_e32 v[134:135], 0
	v_mov_b64_e32 v[136:137], 0
	v_mov_b64_e32 v[138:139], 0
	v_mov_b64_e32 v[140:141], 0
	v_mov_b64_e32 v[142:143], 0
	v_mov_b64_e32 v[144:145], 0
	v_mov_b64_e32 v[146:147], 0
	v_mov_b64_e32 v[148:149], 0
	v_mov_b64_e32 v[150:151], 0
	v_mov_b64_e32 v[152:153], 0
	v_mov_b64_e32 v[154:155], 0
	v_mov_b64_e32 v[156:157], 0
	v_mov_b64_e32 v[158:159], 0
	v_mov_b64_e32 v[160:161], 0

; template <class Epi, class Sched, bool ALIGN_EPI = false, bool SP2 = false>
; __device__ __forceinline__ void gemm_phase(PG8_LAS unsigned char* lds, const Gemm g, const Sched& S, const Epi& E, const int tid) {
;     ...
; #pragma unroll
;         for (int a = 0; a < 2; ++a)
; #pragma unroll
;             for (int b = 0; b < 2; ++b)
; #pragma unroll
;                 for (int m = 0; m < 4; ++m)
; #pragma unroll
;                     for (int n = 0; n < 2; ++n) acc[a][b][m][n] = (f32x4){0.f, 0.f, 0.f, 0.f};
.LBB0_255:
	s_add_u32 s30, s30, 0x100
	v_mov_b32_e32 v2, 0
	s_addc_u32 s31, s31, 0
	s_mov_b32 s65, -2
	v_mov_b32_e32 v3, v2
	v_mov_b64_e32 v[4:5], 0
	v_mov_b64_e32 v[6:7], 0
	v_mov_b64_e32 v[8:9], 0
	v_mov_b64_e32 v[10:11], 0
	v_mov_b64_e32 v[12:13], 0
	v_mov_b64_e32 v[14:15], 0
	v_mov_b64_e32 v[16:17], 0
	v_mov_b64_e32 v[18:19], 0
	v_mov_b64_e32 v[20:21], 0
	v_mov_b64_e32 v[22:23], 0
	v_mov_b64_e32 v[24:25], 0
	v_mov_b64_e32 v[26:27], 0
	v_mov_b64_e32 v[28:29], 0
	v_mov_b64_e32 v[30:31], 0
	v_mov_b64_e32 v[32:33], 0
	v_mov_b64_e32 v[34:35], 0
	v_mov_b64_e32 v[36:37], 0
	v_mov_b64_e32 v[38:39], 0
	v_mov_b64_e32 v[40:41], 0
	v_mov_b64_e32 v[42:43], 0
	v_mov_b64_e32 v[44:45], 0
	v_mov_b64_e32 v[46:47], 0
	v_mov_b64_e32 v[48:49], 0
	v_mov_b64_e32 v[66:67], 0
	v_mov_b64_e32 v[68:69], 0
	v_mov_b64_e32 v[74:75], 0
	v_mov_b64_e32 v[76:77], 0
	v_mov_b64_e32 v[90:91], 0
	v_mov_b64_e32 v[92:93], 0
	v_mov_b64_e32 v[94:95], 0
	v_mov_b64_e32 v[96:97], 0
	v_mov_b64_e32 v[98:99], 0
	v_mov_b64_e32 v[100:101], 0
	v_mov_b64_e32 v[102:103], 0
	v_mov_b64_e32 v[104:105], 0
	v_mov_b64_e32 v[106:107], 0
	v_mov_b64_e32 v[108:109], 0
	v_mov_b64_e32 v[110:111], 0
	v_mov_b64_e32 v[112:113], 0
	v_mov_b64_e32 v[114:115], 0
	v_mov_b64_e32 v[116:117], 0
	v_mov_b64_e32 v[118:119], 0
	v_mov_b64_e32 v[120:121], 0
	v_mov_b64_e32 v[122:123], 0
	v_mov_b64_e32 v[124:125], 0
	v_mov_b64_e32 v[126:127], 0
	v_mov_b64_e32 v[128:129], 0
	v_mov_b64_e32 v[130:131], 0
	v_mov_b64_e32 v[132:133], 0
	v_mov_b64_e32 v[134:135], 0
	v_mov_b64_e32 v[136:137], 0
	v_mov_b64_e32 v[138:139], 0
	v_mov_b64_e32 v[140:141], 0
	v_mov_b64_e32 v[142:143], 0
	v_mov_b64_e32 v[144:145], 0
	v_mov_b64_e32 v[146:147], 0
	v_mov_b64_e32 v[148:149], 0
	v_mov_b64_e32 v[150:151], 0
	v_mov_b64_e32 v[152:153], 0
	v_mov_b64_e32 v[154:155], 0
	v_mov_b64_e32 v[156:157], 0
	v_mov_b64_e32 v[158:159], 0
	v_mov_b64_e32 v[160:161], 0

; template <class Epi, class Sched, bool ALIGN_EPI = false, bool SP2 = false>
; __device__ __forceinline__ void gemm_phase(PG8_LAS unsigned char* lds, const Gemm g, const Sched& S, const Epi& E, const int tid) {
;     ...
;         const bool has_next = S.next(ui + 1, nxt);
;         const char* nA = has_next ? (const char*)g.A + (size_t)nxt.pm * tstep : cA; const char* nB = has_next ? (const char*)g.Bt + (size_t)nxt.pn * tstep : cB;
;         for (int t = 0; t < nt; t += 2) {
;             const bool last = (t == nt - 2);
;             const char* a1 = cA + (size_t)(t + 1) * kstep;
;             const char* a2 = last ? nA : cA + (size_t)(t + 2) * kstep; const char* b2 = last ? nB : cB + (size_t)(t + 2) * kstep;
;     ...
; #pragma unroll
;         for (int a = 0; a < 2; ++a)
; #pragma unroll
;             for (int b = 0; b < 2; ++b)
; #pragma unroll
;                 for (int m = 0; m < 4; ++m)
; #pragma unroll
;                     for (int n = 0; n < 2; ++n) acc[a][b][m][n] = (f32x4){0.f, 0.f, 0.f, 0.f};
.LBB0_397:
	s_ashr_i32 s39, s38, 31
	s_lshl_b64 s[40:41], s[38:39], 19
	s_add_u32 s40, s94, s40
	s_addc_u32 s41, s95, s41
	s_and_b64 s[52:53], exec, s[2:3]
	s_cselect_b32 s39, s37, s41
	s_cselect_b32 s69, s36, s40
	s_ashr_i32 s11, s10, 31
	s_lshl_b64 s[52:53], s[10:11], 19
	v_readlane_b32 s11, v252, 55
	s_add_u32 s52, s11, s52
	v_readlane_b32 s11, v252, 56
	s_addc_u32 s53, s11, s53
	s_and_b64 s[70:71], exec, s[2:3]
	s_cselect_b32 s11, s31, s53
	s_cselect_b32 s70, s30, s52
	s_add_u32 vcc_lo, s36, 0x40080
	s_addc_u32 vcc_hi, s37, 0
	s_add_u32 s71, s30, 0x100
	v_mov_b32_e32 v2, 0
	s_addc_u32 s72, s31, 0
	s_mov_b32 s73, -2
	v_mov_b32_e32 v3, v2
	v_mov_b64_e32 v[4:5], 0
	v_mov_b64_e32 v[6:7], 0
	v_mov_b64_e32 v[8:9], 0
	v_mov_b64_e32 v[10:11], 0
	v_mov_b64_e32 v[12:13], 0
	v_mov_b64_e32 v[14:15], 0
	v_mov_b64_e32 v[16:17], 0
	v_mov_b64_e32 v[18:19], 0
	v_mov_b64_e32 v[20:21], 0
	v_mov_b64_e32 v[22:23], 0
	v_mov_b64_e32 v[24:25], 0
	v_mov_b64_e32 v[26:27], 0
	v_mov_b64_e32 v[28:29], 0
	v_mov_b64_e32 v[30:31], 0
	v_mov_b64_e32 v[32:33], 0
	v_mov_b64_e32 v[34:35], 0
	v_mov_b64_e32 v[36:37], 0
	v_mov_b64_e32 v[38:39], 0
	v_mov_b64_e32 v[40:41], 0
	v_mov_b64_e32 v[42:43], 0
	v_mov_b64_e32 v[44:45], 0
	v_mov_b64_e32 v[46:47], 0
	v_mov_b64_e32 v[48:49], 0
	v_mov_b64_e32 v[50:51], 0
	v_mov_b64_e32 v[52:53], 0
	v_mov_b64_e32 v[54:55], 0
	v_mov_b64_e32 v[56:57], 0
	v_mov_b64_e32 v[58:59], 0
	v_mov_b64_e32 v[60:61], 0
	v_mov_b64_e32 v[62:63], 0
	v_mov_b64_e32 v[64:65], 0
	v_mov_b64_e32 v[66:67], 0
	v_mov_b64_e32 v[68:69], 0
	v_mov_b64_e32 v[70:71], 0
	v_mov_b64_e32 v[72:73], 0
	v_mov_b64_e32 v[74:75], 0
	v_mov_b64_e32 v[76:77], 0
	v_mov_b64_e32 v[78:79], 0
	v_mov_b64_e32 v[80:81], 0
	v_mov_b64_e32 v[90:91], 0
	v_mov_b64_e32 v[92:93], 0
	v_mov_b64_e32 v[98:99], 0
	v_mov_b64_e32 v[100:101], 0
	v_mov_b64_e32 v[102:103], 0
	v_mov_b64_e32 v[104:105], 0
	v_mov_b64_e32 v[106:107], 0
	v_mov_b64_e32 v[108:109], 0
	v_mov_b64_e32 v[118:119], 0
	v_mov_b64_e32 v[120:121], 0
	v_mov_b64_e32 v[122:123], 0
	v_mov_b64_e32 v[124:125], 0
	v_mov_b64_e32 v[126:127], 0
	v_mov_b64_e32 v[128:129], 0
	v_mov_b64_e32 v[130:131], 0
	v_mov_b64_e32 v[132:133], 0
	v_mov_b64_e32 v[138:139], 0
	v_mov_b64_e32 v[140:141], 0
	v_mov_b64_e32 v[142:143], 0
	v_mov_b64_e32 v[144:145], 0
	v_mov_b64_e32 v[146:147], 0
	v_mov_b64_e32 v[148:149], 0
	v_mov_b64_e32 v[154:155], 0
	v_mov_b64_e32 v[156:157], 0
